# xb1 + thread 0 issues its L1 invalidate (buffer_inv sc1) at arrival instead of after the release; nothing is loaded in between except sc1 polls, so the invalidate latency overlaps the barrier wait
# speedup vs baseline: 1.0364x; 1.0151x over previous
; __device__ __forceinline__ unsigned xb_ld(unsigned* p)              { return __hip_atomic_load(p, __ATOMIC_RELAXED, __HIP_MEMORY_SCOPE_AGENT); }
; __device__ __forceinline__ unsigned xb_add(unsigned* p, unsigned v) { return __hip_atomic_fetch_add(p, v, __ATOMIC_RELAXED, __HIP_MEMORY_SCOPE_AGENT); }
; #define XB_SPIN(cond, bar) do { unsigned _sp = 0; while (cond) { __builtin_amdgcn_s_sleep(1); \
;     if ((++_sp & 255u) == 0u) { if (xb_ld(&(bar)[XB_TMO])) break; if (_sp > XB_SPIN_CAP) { atomicAdd(&(bar)[XB_TMO], 1u); break; } } } } while (0)
; __device__ __forceinline__ void xcd_barrier(const XcdBarrier& b) {
;     asm volatile("s_waitcnt vmcnt(0)" ::: "memory");
;     __syncthreads();
;     if (threadIdx.x == 0) {
;         unsigned* bar = b.bar;
;         __builtin_amdgcn_s_waitcnt(0);
;         unsigned nloc = b.st[0], nx = b.st[1];
;         if (nloc == 0u) { xcd_barrier_complete(bar, b.x, nloc, nx); b.st[0] = nloc; b.st[1] = nx; }
;         const unsigned old = xb_add(&bar[XB_XSUB(b.x)], 1u);
;         const unsigned gen = old / nloc;
;         if (old + 1u == (gen + 1u) * nloc) {
;             __builtin_amdgcn_fence(__ATOMIC_RELEASE, "agent");
;             asm volatile("s_waitcnt vmcnt(0)" ::: "memory");
;             const unsigned og = xb_add(&bar[XB_TOP], 1u);
;             const unsigned tg = og / nx;
;             if (og + 1u == (tg + 1u) * nx) xb_add(&bar[XB_TOPGEN], 1u);
;             else XB_SPIN(xb_ld(&bar[XB_TOPGEN]) == tg, bar);
;             __builtin_amdgcn_fence(__ATOMIC_ACQUIRE, "agent");
;             xb_add(&bar[XB_XGEN(b.x)], 1u);
;             asm volatile("s_waitcnt vmcnt(0)" ::: "memory");
;         } else {
;             XB_SPIN(xb_ld(&bar[XB_XGEN(b.x)]) == gen, bar);
;             __builtin_amdgcn_fence(__ATOMIC_ACQUIRE, "agent");
;             asm volatile("s_waitcnt vmcnt(0)" ::: "memory");
;         }
;     }
;     __syncthreads();
.LBB0_207:
	s_getreg_b32 s2, hwreg(HW_REG_XCC_ID, 0, 4)
	s_waitcnt vmcnt(0)
	s_barrier
	s_mov_b64 s[0:1], exec
	v_readlane_b32 s4, v253, 2
	v_readlane_b32 s5, v253, 3
	s_and_b64 s[4:5], s[0:1], s[4:5]
	s_mov_b64 exec, s[4:5]
	s_cbranch_execz .LBB0_259
	v_mov_b32_e32 v0, 0x20020
	s_waitcnt vmcnt(0) lgkmcnt(0)
	ds_read2_b32 v[2:3], v0 offset1:1
	s_and_b32 s3, s2, 15
	s_lshl_b32 s3, s3, 8
	s_add_u32 s6, s78, 0x1701400
	s_addc_u32 s7, s79, 0
	s_add_u32 s6, s6, s3
	s_addc_u32 s7, s7, 0
	s_add_u32 s8, s6, 0x1000
	s_addc_u32 s9, s7, 0
	s_add_u32 s10, s78, 0x1703400
	s_addc_u32 s11, s79, 0
	s_waitcnt lgkmcnt(0)
	v_readfirstlane_b32 s30, v2
	v_readfirstlane_b32 s31, v3
	s_nop 3
	s_cmp_eq_u32 s30, 0
	s_cbranch_scc1 .Lxb_slow_n
	s_lshl_b32 s29, s66, 2
	s_add_i32 s29, s29, 1
	global_atomic_add v2, v173, v212, s[6:7] sc0
	buffer_inv sc1
	s_add_i32 s32, s29, 1
	s_mul_i32 s5, s32, s30
	s_mul_i32 s32, s32, s31
	s_waitcnt vmcnt(1)
	v_readfirstlane_b32 s3, v2
	s_nop 3
	s_add_i32 s3, s3, 1
	s_cmp_lg_u32 s3, s5
	s_cbranch_scc1 .Lxb_local_n
	buffer_wbl2 sc1
	s_waitcnt vmcnt(0)
	global_atomic_add v173, v212, s[10:11]
	s_mov_b32 s3, 0

; __device__ __forceinline__ unsigned xb_add(unsigned* p, unsigned v) { return __hip_atomic_fetch_add(p, v, __ATOMIC_RELAXED, __HIP_MEMORY_SCOPE_AGENT); }
; __device__ __forceinline__ void xcd_barrier(const XcdBarrier& b) {
;     ...
;             __builtin_amdgcn_fence(__ATOMIC_ACQUIRE, "agent");
;             xb_add(&bar[XB_XGEN(b.x)], 1u);
;             asm volatile("s_waitcnt vmcnt(0)" ::: "memory");
.Lxb_top_n_done:
	global_atomic_add v173, v212, s[8:9]
	s_branch .LBB0_259

; __device__ __forceinline__ unsigned xb_ld(unsigned* p)              { return __hip_atomic_load(p, __ATOMIC_RELAXED, __HIP_MEMORY_SCOPE_AGENT); }
; #define XB_SPIN(cond, bar) do { unsigned _sp = 0; while (cond) { __builtin_amdgcn_s_sleep(1); \
;     if ((++_sp & 255u) == 0u) { if (xb_ld(&(bar)[XB_TMO])) break; if (_sp > XB_SPIN_CAP) { atomicAdd(&(bar)[XB_TMO], 1u); break; } } } } while (0)
; __device__ __forceinline__ void xcd_barrier(const XcdBarrier& b) {
;     ...
;             XB_SPIN(xb_ld(&bar[XB_XGEN(b.x)]) == gen, bar);
;             __builtin_amdgcn_fence(__ATOMIC_ACQUIRE, "agent");
;             asm volatile("s_waitcnt vmcnt(0)" ::: "memory");
.Lxb_gen_n_done:
	s_waitcnt vmcnt(0)
	s_branch .LBB0_259

; __device__ __forceinline__ unsigned xb_ld(unsigned* p)              { return __hip_atomic_load(p, __ATOMIC_RELAXED, __HIP_MEMORY_SCOPE_AGENT); }
; __device__ __forceinline__ unsigned xb_add(unsigned* p, unsigned v) { return __hip_atomic_fetch_add(p, v, __ATOMIC_RELAXED, __HIP_MEMORY_SCOPE_AGENT); }
; #define XB_SPIN(cond, bar) do { unsigned _sp = 0; while (cond) { __builtin_amdgcn_s_sleep(1); \
;     if ((++_sp & 255u) == 0u) { if (xb_ld(&(bar)[XB_TMO])) break; if (_sp > XB_SPIN_CAP) { atomicAdd(&(bar)[XB_TMO], 1u); break; } } } } while (0)
; __device__ __forceinline__ void xcd_barrier(const XcdBarrier& b) {
;     asm volatile("s_waitcnt vmcnt(0)" ::: "memory");
;     __syncthreads();
;     if (threadIdx.x == 0) {
;         unsigned* bar = b.bar;
;         __builtin_amdgcn_s_waitcnt(0);
;         unsigned nloc = b.st[0], nx = b.st[1];
;         if (nloc == 0u) { xcd_barrier_complete(bar, b.x, nloc, nx); b.st[0] = nloc; b.st[1] = nx; }
;         const unsigned old = xb_add(&bar[XB_XSUB(b.x)], 1u);
;         const unsigned gen = old / nloc;
;         if (old + 1u == (gen + 1u) * nloc) {
;             __builtin_amdgcn_fence(__ATOMIC_RELEASE, "agent");
;             asm volatile("s_waitcnt vmcnt(0)" ::: "memory");
;             const unsigned og = xb_add(&bar[XB_TOP], 1u);
;             const unsigned tg = og / nx;
;             if (og + 1u == (tg + 1u) * nx) xb_add(&bar[XB_TOPGEN], 1u);
;             else XB_SPIN(xb_ld(&bar[XB_TOPGEN]) == tg, bar);
;             __builtin_amdgcn_fence(__ATOMIC_ACQUIRE, "agent");
;             xb_add(&bar[XB_XGEN(b.x)], 1u);
;             asm volatile("s_waitcnt vmcnt(0)" ::: "memory");
;         } else {
;             XB_SPIN(xb_ld(&bar[XB_XGEN(b.x)]) == gen, bar);
;             __builtin_amdgcn_fence(__ATOMIC_ACQUIRE, "agent");
;             asm volatile("s_waitcnt vmcnt(0)" ::: "memory");
;         }
;     }
;     __syncthreads();
.LBB0_386:
	s_getreg_b32 s2, hwreg(HW_REG_XCC_ID, 0, 4)
	s_waitcnt vmcnt(0)
	v_writelane_b32 v255, s0, 13
	s_waitcnt vmcnt(0)
	s_barrier
	v_writelane_b32 v255, s1, 14
	s_mov_b64 s[0:1], exec
	v_readlane_b32 s4, v253, 2
	v_readlane_b32 s5, v253, 3
	s_and_b64 s[4:5], s[0:1], s[4:5]
	s_mov_b64 exec, s[4:5]
	s_cbranch_execz .LBB0_439
	v_mov_b32_e32 v0, 0x20020
	s_waitcnt vmcnt(0) lgkmcnt(0)
	ds_read2_b32 v[2:3], v0 offset1:1
	s_and_b32 s3, s2, 15
	s_lshl_b32 s3, s3, 8
	s_add_u32 s6, s78, 0x1701400
	s_addc_u32 s7, s79, 0
	s_add_u32 s6, s6, s3
	s_addc_u32 s7, s7, 0
	s_add_u32 s8, s6, 0x1000
	s_addc_u32 s9, s7, 0
	s_add_u32 s10, s78, 0x1703400
	s_addc_u32 s11, s79, 0
	s_waitcnt lgkmcnt(0)
	v_readfirstlane_b32 s30, v2
	v_readfirstlane_b32 s31, v3
	s_nop 3
	s_cmp_eq_u32 s30, 0
	s_cbranch_scc1 .Lxb_slow_i
	s_lshl_b32 s29, s66, 2
	s_add_i32 s29, s29, 2
	global_atomic_add v2, v173, v212, s[6:7] sc0
	buffer_inv sc1
	s_add_i32 s32, s29, 1
	s_mul_i32 s5, s32, s30
	s_mul_i32 s32, s32, s31
	s_waitcnt vmcnt(1)
	v_readfirstlane_b32 s3, v2
	s_nop 3
	s_add_i32 s3, s3, 1
	s_cmp_lg_u32 s3, s5
	s_cbranch_scc1 .Lxb_local_i
	buffer_wbl2 sc1
	s_waitcnt vmcnt(0)
	global_atomic_add v173, v212, s[10:11]
	s_mov_b32 s3, 0

; __device__ __forceinline__ unsigned xb_ld(unsigned* p)              { return __hip_atomic_load(p, __ATOMIC_RELAXED, __HIP_MEMORY_SCOPE_AGENT); }
; __device__ __forceinline__ unsigned xb_add(unsigned* p, unsigned v) { return __hip_atomic_fetch_add(p, v, __ATOMIC_RELAXED, __HIP_MEMORY_SCOPE_AGENT); }
; #define XB_SPIN(cond, bar) do { unsigned _sp = 0; while (cond) { __builtin_amdgcn_s_sleep(1); \
;     if ((++_sp & 255u) == 0u) { if (xb_ld(&(bar)[XB_TMO])) break; if (_sp > XB_SPIN_CAP) { atomicAdd(&(bar)[XB_TMO], 1u); break; } } } } while (0)
; __device__ __forceinline__ void xcd_barrier(const XcdBarrier& b) {
;     asm volatile("s_waitcnt vmcnt(0)" ::: "memory");
;     __syncthreads();
;     if (threadIdx.x == 0) {
;         unsigned* bar = b.bar;
;         __builtin_amdgcn_s_waitcnt(0);
;         unsigned nloc = b.st[0], nx = b.st[1];
;         if (nloc == 0u) { xcd_barrier_complete(bar, b.x, nloc, nx); b.st[0] = nloc; b.st[1] = nx; }
;         const unsigned old = xb_add(&bar[XB_XSUB(b.x)], 1u);
;         const unsigned gen = old / nloc;
;         if (old + 1u == (gen + 1u) * nloc) {
;             __builtin_amdgcn_fence(__ATOMIC_RELEASE, "agent");
;             asm volatile("s_waitcnt vmcnt(0)" ::: "memory");
;             const unsigned og = xb_add(&bar[XB_TOP], 1u);
;             const unsigned tg = og / nx;
;             if (og + 1u == (tg + 1u) * nx) xb_add(&bar[XB_TOPGEN], 1u);
;             else XB_SPIN(xb_ld(&bar[XB_TOPGEN]) == tg, bar);
;             __builtin_amdgcn_fence(__ATOMIC_ACQUIRE, "agent");
;             xb_add(&bar[XB_XGEN(b.x)], 1u);
;             asm volatile("s_waitcnt vmcnt(0)" ::: "memory");
;         } else {
;             XB_SPIN(xb_ld(&bar[XB_XGEN(b.x)]) == gen, bar);
;             __builtin_amdgcn_fence(__ATOMIC_ACQUIRE, "agent");
;             asm volatile("s_waitcnt vmcnt(0)" ::: "memory");
;         }
;     }
;     __syncthreads();
.LBB0_534:
	s_and_b64 vcc, exec, s[0:1]
	s_mov_b32 s93, s4
	s_cbranch_vccz .LBB0_441
	s_getreg_b32 s2, hwreg(HW_REG_XCC_ID, 0, 4)
	s_waitcnt vmcnt(0)
	s_barrier
	s_mov_b64 s[0:1], exec
	v_readlane_b32 s4, v253, 2
	v_readlane_b32 s5, v253, 3
	v_readlane_b32 s72, v254, 48
	v_readlane_b32 s80, v254, 50
	v_readlane_b32 s82, v254, 52
	v_readlane_b32 s92, v254, 54
	v_readlane_b32 s94, v254, 56
	v_readlane_b32 s98, v254, 58
	v_readlane_b32 s54, v254, 60
	v_readlane_b32 s56, v254, 62
	v_readlane_b32 s60, v255, 0
	v_readlane_b32 s62, v255, 2
	v_readlane_b32 s22, v255, 21
	s_and_b64 s[4:5], s[0:1], s[4:5]
	v_readlane_b32 s73, v254, 49
	v_readlane_b32 s81, v254, 51
	v_readlane_b32 s83, v254, 53
	v_readlane_b32 s93, v254, 55
	v_readlane_b32 s95, v254, 57
	v_readlane_b32 s99, v254, 59
	v_readlane_b32 s55, v254, 61
	v_readlane_b32 s57, v254, 63
	v_readlane_b32 s61, v255, 1
	v_readlane_b32 s63, v255, 3
	v_readlane_b32 s33, v255, 4
	v_readlane_b32 s85, v255, 5
	v_readlane_b32 s25, v254, 41
	v_readlane_b32 s28, v254, 43
	v_readlane_b32 s23, v255, 22
	s_mov_b64 exec, s[4:5]
	s_cbranch_execz .LBB0_587
	v_mov_b32_e32 v0, 0x20020
	s_waitcnt vmcnt(0) lgkmcnt(0)
	ds_read2_b32 v[2:3], v0 offset1:1
	s_and_b32 s3, s2, 15
	s_lshl_b32 s3, s3, 8
	s_add_u32 s6, s78, 0x1701400
	s_addc_u32 s7, s79, 0
	s_add_u32 s6, s6, s3
	s_addc_u32 s7, s7, 0
	s_add_u32 s8, s6, 0x1000
	s_addc_u32 s9, s7, 0
	s_add_u32 s10, s78, 0x1703400
	s_addc_u32 s11, s79, 0
	s_waitcnt lgkmcnt(0)
	v_readfirstlane_b32 s30, v2
	v_readfirstlane_b32 s31, v3
	s_nop 3
	s_cmp_eq_u32 s30, 0
	s_cbranch_scc1 .Lxb_slow_m
	v_readlane_b32 s29, v255, 21
	s_nop 3
	s_lshl_b32 s29, s29, 2
	s_add_i32 s29, s29, 3
	global_atomic_add v2, v173, v212, s[6:7] sc0
	buffer_inv sc1
	s_add_i32 s32, s29, 1
	s_mul_i32 s5, s32, s30
	s_mul_i32 s32, s32, s31
	s_waitcnt vmcnt(1)
	v_readfirstlane_b32 s3, v2
	s_nop 3
	s_add_i32 s3, s3, 1
	s_cmp_lg_u32 s3, s5
	s_cbranch_scc1 .Lxb_local_m
	buffer_wbl2 sc1
	s_waitcnt vmcnt(0)
	global_atomic_add v173, v212, s[10:11]
	s_mov_b32 s3, 0

; __device__ __forceinline__ unsigned xb_ld(unsigned* p)              { return __hip_atomic_load(p, __ATOMIC_RELAXED, __HIP_MEMORY_SCOPE_AGENT); }
; __device__ __forceinline__ unsigned xb_add(unsigned* p, unsigned v) { return __hip_atomic_fetch_add(p, v, __ATOMIC_RELAXED, __HIP_MEMORY_SCOPE_AGENT); }
; #define XB_SPIN(cond, bar) do { unsigned _sp = 0; while (cond) { __builtin_amdgcn_s_sleep(1); \
;     if ((++_sp & 255u) == 0u) { if (xb_ld(&(bar)[XB_TMO])) break; if (_sp > XB_SPIN_CAP) { atomicAdd(&(bar)[XB_TMO], 1u); break; } } } } while (0)
; __device__ __forceinline__ void xcd_barrier(const XcdBarrier& b) {
;     asm volatile("s_waitcnt vmcnt(0)" ::: "memory");
;     __syncthreads();
;     if (threadIdx.x == 0) {
;         unsigned* bar = b.bar;
;         __builtin_amdgcn_s_waitcnt(0);
;         unsigned nloc = b.st[0], nx = b.st[1];
;         if (nloc == 0u) { xcd_barrier_complete(bar, b.x, nloc, nx); b.st[0] = nloc; b.st[1] = nx; }
;         const unsigned old = xb_add(&bar[XB_XSUB(b.x)], 1u);
;         const unsigned gen = old / nloc;
;         if (old + 1u == (gen + 1u) * nloc) {
;             __builtin_amdgcn_fence(__ATOMIC_RELEASE, "agent");
;             asm volatile("s_waitcnt vmcnt(0)" ::: "memory");
;             const unsigned og = xb_add(&bar[XB_TOP], 1u);
;             const unsigned tg = og / nx;
;             if (og + 1u == (tg + 1u) * nx) xb_add(&bar[XB_TOPGEN], 1u);
;             else XB_SPIN(xb_ld(&bar[XB_TOPGEN]) == tg, bar);
;             __builtin_amdgcn_fence(__ATOMIC_ACQUIRE, "agent");
;             xb_add(&bar[XB_XGEN(b.x)], 1u);
;             asm volatile("s_waitcnt vmcnt(0)" ::: "memory");
;         } else {
;             XB_SPIN(xb_ld(&bar[XB_XGEN(b.x)]) == gen, bar);
;             __builtin_amdgcn_fence(__ATOMIC_ACQUIRE, "agent");
;             asm volatile("s_waitcnt vmcnt(0)" ::: "memory");
;         }
;     }
;     __syncthreads();
.LBB0_683:
	v_readlane_b32 s2, v255, 11
	v_readlane_b32 s3, v255, 12
	s_mov_b64 s[0:1], -1
	s_and_b64 vcc, exec, s[2:3]
	v_readlane_b32 s12, v255, 6
	s_mov_b64 s[26:27], 0x1000
	v_readlane_b32 s13, v255, 7
	s_cbranch_vccz .LBB0_190
	s_getreg_b32 s2, hwreg(HW_REG_XCC_ID, 0, 4)
	s_waitcnt vmcnt(0)
	s_barrier
	s_mov_b64 s[0:1], exec
	v_readlane_b32 s4, v253, 2
	v_readlane_b32 s5, v253, 3
	s_and_b64 s[4:5], s[0:1], s[4:5]
	s_mov_b64 exec, s[4:5]
	s_cbranch_execz .LBB0_189
	v_mov_b32_e32 v0, 0x20020
	s_waitcnt vmcnt(0) lgkmcnt(0)
	ds_read2_b32 v[2:3], v0 offset1:1
	s_and_b32 s3, s2, 15
	s_lshl_b32 s3, s3, 8
	s_add_u32 s6, s78, 0x1701400
	s_addc_u32 s7, s79, 0
	s_add_u32 s6, s6, s3
	s_addc_u32 s7, s7, 0
	s_add_u32 s8, s6, 0x1000
	s_addc_u32 s9, s7, 0
	s_add_u32 s10, s78, 0x1703400
	s_addc_u32 s11, s79, 0
	s_waitcnt lgkmcnt(0)
	v_readfirstlane_b32 s30, v2
	v_readfirstlane_b32 s31, v3
	s_nop 3
	s_cmp_eq_u32 s30, 0
	s_cbranch_scc1 .Lxb_slow_o
	s_mov_b32 s29, 4
	global_atomic_add v2, v173, v212, s[6:7] sc0
	buffer_inv sc1
	s_add_i32 s32, s29, 1
	s_mul_i32 s5, s32, s30
	s_mul_i32 s32, s32, s31
	s_waitcnt vmcnt(1)
	v_readfirstlane_b32 s3, v2
	s_nop 3
	s_add_i32 s3, s3, 1
	s_cmp_lg_u32 s3, s5
	s_cbranch_scc1 .Lxb_local_o
	buffer_wbl2 sc1
	s_waitcnt vmcnt(0)
	global_atomic_add v173, v212, s[10:11]
	s_mov_b32 s3, 0
